# plus: cmp2 hidden-layer Y loads batched, convert_late item order reversed, SGU main-step W/V loads hoisted per tile row with counted waits
# speedup vs baseline: 1.0076x; 1.0076x over previous
.LBB0_783:
	s_or_b64 exec, exec, s[58:59]
	v_cvt_pk_bf16_f32 v34, v41, v36
	v_cvt_pk_bf16_f32 v35, v40, v38
	v_cvt_pk_bf16_f32 v36, v37, v39
	global_load_dwordx4 v[38:41], v[98:99], off offset:-96
	global_load_dwordx4 v[42:45], v[100:101], off offset:-96
	v_cvt_pk_bf16_f32 v37, v32, v33
	v_lshl_add_u64 v[102:103], v[94:95], 0, s[54:55]
	s_brev_b32 s51, 48
	global_load_dword v32, v[76:77], off
	s_waitcnt vmcnt(2)
	v_mfma_f32_32x32x16_bf16 v[16:31], v[38:41], v[34:37], v[16:31]
	s_waitcnt vmcnt(0)
	s_nop 10
	v_pk_add_f32 v[16:17], v[16:17], v[32:33] op_sel_hi:[1,0]
	v_mfma_f32_32x32x16_bf16 v[0:15], v[42:45], v[34:37], v[0:15]
	v_add_co_u32_e32 v34, vcc, s51, v102
	v_add_f32_e64 v18, v18, v32
	v_add_f32_e64 v19, v19, v32
	v_addc_co_u32_e32 v35, vcc, 0, v103, vcc
	global_load_dwordx2 v[116:117], v[34:35], off
	global_load_dwordx2 v[118:119], v[34:35], off offset:16
	global_load_dwordx2 v[120:121], v[34:35], off offset:32
	global_load_dwordx2 v[122:123], v[34:35], off offset:48
	global_load_dwordx2 v[124:125], v[34:35], off offset:64
	global_load_dwordx2 v[126:127], v[34:35], off offset:80
	global_load_dwordx2 v[128:129], v[34:35], off offset:96
	global_load_dwordx2 v[130:131], v[34:35], off offset:112
	s_mov_b32 s51, 0x1a000000
	v_pk_add_f32 v[20:21], v[20:21], v[32:33] op_sel_hi:[1,0]
	v_pk_add_f32 v[22:23], v[22:23], v[32:33] op_sel_hi:[1,0]
	s_nop 3
	v_pk_add_f32 v[0:1], v[32:33], v[0:1] op_sel_hi:[0,1]
	v_pk_add_f32 v[2:3], v[32:33], v[2:3] op_sel_hi:[0,1]
	v_pk_add_f32 v[4:5], v[32:33], v[4:5] op_sel_hi:[0,1]
	s_waitcnt vmcnt(7)
	v_lshlrev_b32_e32 v38, 16, v116
	v_and_b32_e32 v39, 0xffff0000, v116
	v_pk_mul_f32 v[16:17], v[16:17], v[38:39]
	s_nop 0
	v_cvt_pk_bf16_f32 v36, v16, v17
	v_lshlrev_b32_e32 v16, 16, v117
	v_and_b32_e32 v17, 0xffff0000, v117
	v_pk_mul_f32 v[16:17], v[18:19], v[16:17]
	v_cvt_pk_bf16_f32 v37, v16, v17
	v_add_co_u32_e32 v16, vcc, s51, v102
	s_nop 1
	v_addc_co_u32_e32 v17, vcc, 0, v103, vcc
	global_store_dwordx2 v[16:17], v[36:37], off
	s_waitcnt vmcnt(7)
	v_lshlrev_b32_e32 v36, 16, v118
	v_and_b32_e32 v37, 0xffff0000, v118
	v_pk_mul_f32 v[20:21], v[20:21], v[36:37]
	s_nop 0
	v_cvt_pk_bf16_f32 v18, v20, v21
	v_lshlrev_b32_e32 v20, 16, v119
	v_and_b32_e32 v21, 0xffff0000, v119
	v_pk_mul_f32 v[20:21], v[22:23], v[20:21]
	v_pk_add_f32 v[22:23], v[24:25], v[32:33] op_sel_hi:[1,0]
	v_cvt_pk_bf16_f32 v19, v20, v21
	global_store_dwordx2 v[16:17], v[18:19], off offset:16
	s_waitcnt vmcnt(7)
	v_lshlrev_b32_e32 v20, 16, v120
	v_and_b32_e32 v21, 0xffff0000, v120
	v_pk_mul_f32 v[20:21], v[22:23], v[20:21]
	v_pk_add_f32 v[22:23], v[26:27], v[32:33] op_sel_hi:[1,0]
	v_cvt_pk_bf16_f32 v18, v20, v21
	v_lshlrev_b32_e32 v20, 16, v121
	v_and_b32_e32 v21, 0xffff0000, v121
	v_pk_mul_f32 v[20:21], v[22:23], v[20:21]
	v_pk_add_f32 v[22:23], v[28:29], v[32:33] op_sel_hi:[1,0]
	v_cvt_pk_bf16_f32 v19, v20, v21
	global_store_dwordx2 v[16:17], v[18:19], off offset:32
	s_waitcnt vmcnt(7)
	v_lshlrev_b32_e32 v20, 16, v122
	v_and_b32_e32 v21, 0xffff0000, v122
	v_pk_mul_f32 v[20:21], v[22:23], v[20:21]
	v_pk_add_f32 v[22:23], v[30:31], v[32:33] op_sel_hi:[1,0]
	v_cvt_pk_bf16_f32 v18, v20, v21
	v_lshlrev_b32_e32 v20, 16, v123
	v_and_b32_e32 v21, 0xffff0000, v123
	v_pk_mul_f32 v[20:21], v[22:23], v[20:21]
	s_nop 0
	v_cvt_pk_bf16_f32 v19, v20, v21
	global_store_dwordx2 v[16:17], v[18:19], off offset:48
	s_waitcnt vmcnt(7)
	v_lshlrev_b32_e32 v20, 16, v124
	v_and_b32_e32 v21, 0xffff0000, v124
	v_lshlrev_b32_e32 v18, 16, v125
	v_and_b32_e32 v19, 0xffff0000, v125
	v_pk_mul_f32 v[0:1], v[0:1], v[20:21]
	v_pk_mul_f32 v[2:3], v[2:3], v[18:19]
	v_cvt_pk_bf16_f32 v0, v0, v1
	v_cvt_pk_bf16_f32 v1, v2, v3
	global_store_dwordx2 v[16:17], v[0:1], off offset:64
	s_waitcnt vmcnt(7)
	v_lshlrev_b32_e32 v2, 16, v126
	v_and_b32_e32 v3, 0xffff0000, v126
	v_pk_mul_f32 v[2:3], v[4:5], v[2:3]
	v_pk_add_f32 v[4:5], v[32:33], v[6:7] op_sel_hi:[0,1]
	v_cvt_pk_bf16_f32 v0, v2, v3
	v_lshlrev_b32_e32 v2, 16, v127
	v_and_b32_e32 v3, 0xffff0000, v127
	v_pk_mul_f32 v[2:3], v[4:5], v[2:3]
	v_pk_add_f32 v[4:5], v[32:33], v[8:9] op_sel_hi:[0,1]
	v_cvt_pk_bf16_f32 v1, v2, v3
	global_store_dwordx2 v[16:17], v[0:1], off offset:80
	s_waitcnt vmcnt(7)
	v_lshlrev_b32_e32 v2, 16, v128
	v_and_b32_e32 v3, 0xffff0000, v128
	v_pk_mul_f32 v[2:3], v[4:5], v[2:3]
	v_pk_add_f32 v[4:5], v[32:33], v[10:11] op_sel_hi:[0,1]
	v_cvt_pk_bf16_f32 v0, v2, v3
	v_lshlrev_b32_e32 v2, 16, v129
	v_and_b32_e32 v3, 0xffff0000, v129
	v_pk_mul_f32 v[2:3], v[4:5], v[2:3]
	v_pk_add_f32 v[4:5], v[32:33], v[12:13] op_sel_hi:[0,1]
	v_cvt_pk_bf16_f32 v1, v2, v3
	global_store_dwordx2 v[16:17], v[0:1], off offset:96
	s_waitcnt vmcnt(7)
	v_lshlrev_b32_e32 v2, 16, v130
	v_and_b32_e32 v3, 0xffff0000, v130
	v_pk_mul_f32 v[2:3], v[4:5], v[2:3]
	v_pk_add_f32 v[4:5], v[32:33], v[14:15] op_sel_hi:[0,1]
	v_cvt_pk_bf16_f32 v0, v2, v3
	v_lshlrev_b32_e32 v2, 16, v131
	v_and_b32_e32 v3, 0xffff0000, v131
	v_pk_mul_f32 v[2:3], v[4:5], v[2:3]
	s_nop 0
	v_cvt_pk_bf16_f32 v1, v2, v3
	global_store_dwordx2 v[16:17], v[0:1], off offset:112
	global_load_dwordx4 v[116:119], v[78:79], off offset:16
	global_load_dwordx4 v[120:123], v[78:79], off
	global_load_dwordx4 v[124:127], v[98:99], off offset:-128
	global_load_dwordx4 v[128:131], v[100:101], off offset:-128
	global_load_dwordx4 v[136:139], v[78:79], off offset:80
	global_load_dwordx4 v[140:143], v[78:79], off offset:64
	global_load_dwordx4 v[144:147], v[98:99], off offset:-96
	global_load_dwordx4 v[148:151], v[100:101], off offset:-96
	global_load_dwordx4 v[152:155], v[78:79], off offset:144
	global_load_dwordx4 v[156:159], v[78:79], off offset:128
	global_load_dwordx4 v[160:163], v[98:99], off offset:-64
	global_load_dwordx4 v[164:167], v[100:101], off offset:-64
	global_load_dwordx4 v[184:187], v[78:79], off offset:208
	global_load_dwordx4 v[188:191], v[78:79], off offset:192
	global_load_dwordx4 v[192:195], v[98:99], off offset:-32
	global_load_dwordx4 v[196:199], v[100:101], off offset:-32
	s_nop 0
	ds_read_b128 v[36:39], v105
	ds_read_b128 v[32:35], v105 offset:16
	s_waitcnt vmcnt(15) lgkmcnt(0)
	v_pk_mul_f32 v[8:9], v[116:117], v[32:33]
	s_waitcnt vmcnt(14)
	v_pk_mul_f32 v[4:5], v[120:121], v[36:37]
	v_pk_mul_f32 v[6:7], v[122:123], v[38:39]
	v_pk_mul_f32 v[10:11], v[118:119], v[34:35]
	v_cvt_pk_bf16_f32 v0, v4, v5
	v_cvt_pk_bf16_f32 v1, v6, v7
	v_cvt_pk_bf16_f32 v2, v8, v9
	v_cvt_pk_bf16_f32 v3, v10, v11
	ds_read_b128 v[40:43], v105 offset:64
	s_waitcnt vmcnt(13)
	v_mfma_f32_32x32x16_bf16 v[16:31], v[124:127], v[0:3], 0
	s_waitcnt vmcnt(10) lgkmcnt(0)
	v_mul_f32_e64 v52, v140, v40
	v_mul_f32_e64 v53, v141, v41
	v_mul_f32_e64 v54, v142, v42
	v_mul_f32_e64 v55, v143, v43
	ds_read_b128 v[44:47], v105 offset:80
	s_waitcnt lgkmcnt(0)
	v_pk_mul_f32 v[58:59], v[136:137], v[44:45]
	v_pk_mul_f32 v[60:61], v[138:139], v[46:47]
	v_cvt_pk_bf16_f32 v48, v52, v53
	v_cvt_pk_bf16_f32 v49, v54, v55
	v_cvt_pk_bf16_f32 v50, v58, v59
	v_cvt_pk_bf16_f32 v51, v60, v61
	v_mfma_f32_32x32x16_bf16 v[0:15], v[128:131], v[0:3], 0
	s_waitcnt vmcnt(9)
	v_mfma_f32_32x32x16_bf16 v[16:31], v[144:147], v[48:51], v[16:31]
	s_waitcnt vmcnt(8)
	v_mfma_f32_32x32x16_bf16 v[0:15], v[148:151], v[48:51], v[0:15]
	s_mov_b64 s[58:59], exec
	v_readlane_b32 s80, v254, 49
	v_readlane_b32 s81, v254, 50
	s_and_b64 s[80:81], s[58:59], s[80:81]
	s_mov_b64 exec, s[80:81]
	s_cbranch_execz .LBB0_785
	ds_read_b32 v56, v105 offset:128
	s_waitcnt vmcnt(6) lgkmcnt(0)
	v_mul_f32_e32 v56, v156, v56
.LBB0_785:
	s_or_b64 exec, exec, s[58:59]
	s_waitcnt vmcnt(6)
	v_mov_b32_e32 v52, 0
	v_mov_b32_e32 v58, 0
	s_mov_b64 s[58:59], exec
	v_readlane_b32 s80, v254, 51
	v_readlane_b32 s81, v254, 52
	s_and_b64 s[80:81], s[58:59], s[80:81]
	s_mov_b64 exec, s[80:81]
	s_cbranch_execz .LBB0_787
	ds_read_b32 v57, v105 offset:132
	s_waitcnt lgkmcnt(0)
	v_mul_f32_e32 v58, v157, v57
.LBB0_787:
	s_or_b64 exec, exec, s[58:59]
	s_mov_b64 s[58:59], exec
	v_readlane_b32 s80, v254, 53
	v_readlane_b32 s81, v254, 54
	s_and_b64 s[80:81], s[58:59], s[80:81]
	s_mov_b64 exec, s[80:81]
	s_cbranch_execz .LBB0_789
	ds_read_b32 v52, v105 offset:136
	s_waitcnt lgkmcnt(0)
	v_mul_f32_e32 v52, v158, v52
.LBB0_789:
	s_or_b64 exec, exec, s[58:59]
	v_mov_b32_e32 v53, 0
	v_mov_b32_e32 v54, 0
	s_mov_b64 s[58:59], exec
	v_readlane_b32 s80, v254, 55
	v_readlane_b32 s81, v254, 56
	s_and_b64 s[80:81], s[58:59], s[80:81]
	s_mov_b64 exec, s[80:81]
	s_cbranch_execz .LBB0_791
	ds_read_b32 v54, v105 offset:140
	s_waitcnt lgkmcnt(0)
	v_mul_f32_e32 v54, v159, v54
.LBB0_791:
	s_or_b64 exec, exec, s[58:59]
	s_mov_b64 s[58:59], exec
	v_readlane_b32 s80, v254, 57
	v_readlane_b32 s81, v254, 58
	s_and_b64 s[80:81], s[58:59], s[80:81]
	s_mov_b64 exec, s[80:81]
	s_cbranch_execz .LBB0_793
	ds_read_b32 v53, v105 offset:144
	s_waitcnt lgkmcnt(0)
	v_mul_f32_e32 v53, v152, v53
.LBB0_793:
	s_or_b64 exec, exec, s[58:59]
	v_mov_b32_e32 v48, 0
	v_mov_b32_e32 v55, 0
	s_mov_b64 s[58:59], exec
	v_readlane_b32 s80, v254, 59
	v_readlane_b32 s81, v254, 60
	s_and_b64 s[80:81], s[58:59], s[80:81]
	s_mov_b64 exec, s[80:81]
	s_cbranch_execz .LBB0_795
	ds_read_b32 v55, v105 offset:148
	s_waitcnt lgkmcnt(0)
	v_mul_f32_e32 v55, v153, v55
.LBB0_795:
	s_or_b64 exec, exec, s[58:59]
	s_mov_b64 s[58:59], exec
	v_readlane_b32 s80, v254, 61
	v_readlane_b32 s81, v254, 62
	s_and_b64 s[80:81], s[58:59], s[80:81]
	s_mov_b64 exec, s[80:81]
	s_cbranch_execz .LBB0_797
	ds_read_b32 v48, v105 offset:152
	s_waitcnt lgkmcnt(0)
	v_mul_f32_e32 v48, v154, v48
.LBB0_797:
	s_or_b64 exec, exec, s[58:59]
	v_mov_b32_e32 v57, 0
	v_mov_b32_e32 v49, 0
	s_mov_b64 s[58:59], exec
	v_readlane_b32 s80, v254, 63
	v_readlane_b32 s81, v255, 0
	s_and_b64 s[80:81], s[58:59], s[80:81]
	s_mov_b64 exec, s[80:81]
	s_cbranch_execz .LBB0_799
	ds_read_b32 v49, v105 offset:156
	s_waitcnt lgkmcnt(0)
	v_mul_f32_e32 v49, v155, v49
.LBB0_799:
	s_or_b64 exec, exec, s[58:59]
	v_cvt_pk_bf16_f32 v50, v56, v58
	v_cvt_pk_bf16_f32 v51, v52, v54
	v_cvt_pk_bf16_f32 v52, v53, v55
	v_cvt_pk_bf16_f32 v53, v48, v49
	s_waitcnt vmcnt(5)
	s_nop 0
	v_mfma_f32_32x32x16_bf16 v[16:31], v[160:163], v[50:53], v[16:31]
	s_waitcnt vmcnt(4)
	v_mfma_f32_32x32x16_bf16 v[0:15], v[164:167], v[50:53], v[0:15]
	s_mov_b64 s[58:59], exec
	v_readlane_b32 s80, v255, 1
	v_readlane_b32 s81, v255, 2
	s_and_b64 s[80:81], s[58:59], s[80:81]
	s_mov_b64 exec, s[80:81]
	s_cbranch_execz .LBB0_801
	ds_read_b32 v56, v105 offset:192
	s_waitcnt vmcnt(2) lgkmcnt(0)
	v_mul_f32_e32 v57, v188, v56
.LBB0_801:
	s_or_b64 exec, exec, s[58:59]
	s_waitcnt vmcnt(2)
	v_mov_b32_e32 v52, 0
	v_mov_b32_e32 v56, 0
	s_mov_b64 s[58:59], exec
	v_readlane_b32 s80, v255, 3
	v_readlane_b32 s81, v255, 4
	s_and_b64 s[80:81], s[58:59], s[80:81]
	s_mov_b64 exec, s[80:81]
	s_cbranch_execz .LBB0_803
	ds_read_b32 v56, v105 offset:196
	s_waitcnt lgkmcnt(0)
	v_mul_f32_e32 v56, v189, v56
.LBB0_803:
	s_or_b64 exec, exec, s[58:59]
	s_and_saveexec_b64 s[58:59], s[62:63]
	s_cbranch_execz .LBB0_805
	ds_read_b32 v52, v105 offset:200
	s_waitcnt lgkmcnt(0)
	v_mul_f32_e32 v52, v190, v52
.LBB0_805:
	s_or_b64 exec, exec, s[58:59]
	v_mov_b32_e32 v53, 0
	v_mov_b32_e32 v54, 0
	s_and_saveexec_b64 s[58:59], s[64:65]
	s_cbranch_execz .LBB0_807
	ds_read_b32 v54, v105 offset:204
	s_waitcnt lgkmcnt(0)
	v_mul_f32_e32 v54, v191, v54
.LBB0_807:
	s_or_b64 exec, exec, s[58:59]
	s_and_saveexec_b64 s[58:59], s[66:67]
	s_cbranch_execz .LBB0_809
	ds_read_b32 v53, v105 offset:208
	s_waitcnt lgkmcnt(0)
	v_mul_f32_e32 v53, v184, v53
.LBB0_809:
	s_or_b64 exec, exec, s[58:59]
	v_mov_b32_e32 v48, 0
	v_mov_b32_e32 v55, 0
	s_and_saveexec_b64 s[58:59], s[68:69]
	s_cbranch_execz .LBB0_811
	ds_read_b32 v55, v105 offset:212
	s_waitcnt lgkmcnt(0)
	v_mul_f32_e32 v55, v185, v55
.LBB0_811:
	s_or_b64 exec, exec, s[58:59]
	s_and_saveexec_b64 s[58:59], s[70:71]
	s_cbranch_execz .LBB0_813
	ds_read_b32 v48, v105 offset:216
	s_waitcnt lgkmcnt(0)
	v_mul_f32_e32 v48, v186, v48
.LBB0_813:
	s_or_b64 exec, exec, s[58:59]
	v_mov_b32_e32 v87, 0
	v_mov_b32_e32 v49, 0
	s_and_saveexec_b64 s[58:59], s[72:73]
	s_cbranch_execz .LBB0_815
	ds_read_b32 v49, v105 offset:220
	s_waitcnt lgkmcnt(0)
	v_mul_f32_e32 v49, v187, v49
.LBB0_815:
	s_or_b64 exec, exec, s[58:59]
	v_cvt_pk_bf16_f32 v50, v57, v56
	v_cvt_pk_bf16_f32 v51, v52, v54
	v_cvt_pk_bf16_f32 v52, v53, v55
	v_cvt_pk_bf16_f32 v53, v48, v49
	s_brev_b32 s51, 48
	global_load_dword v48, v[80:81], off
	s_waitcnt vmcnt(2)
	v_mfma_f32_32x32x16_bf16 v[16:31], v[192:195], v[50:53], v[16:31]
	s_waitcnt vmcnt(0)
	s_nop 10
	v_pk_add_f32 v[16:17], v[16:17], v[48:49] op_sel_hi:[1,0]
	v_mfma_f32_32x32x16_bf16 v[0:15], v[196:199], v[50:53], v[0:15]
	v_lshl_add_u64 v[52:53], v[96:97], 0, s[54:55]
	v_add_co_u32_e32 v50, vcc, s51, v52
	v_add_f32_e64 v18, v18, v48
	v_add_f32_e64 v19, v19, v48
	v_addc_co_u32_e32 v51, vcc, 0, v53, vcc
	global_load_dwordx2 v[116:117], v[50:51], off
	global_load_dwordx2 v[118:119], v[50:51], off offset:16
	global_load_dwordx2 v[120:121], v[50:51], off offset:32
	global_load_dwordx2 v[122:123], v[50:51], off offset:48
	global_load_dwordx2 v[124:125], v[50:51], off offset:64
	global_load_dwordx2 v[126:127], v[50:51], off offset:80
	global_load_dwordx2 v[128:129], v[50:51], off offset:96
	global_load_dwordx2 v[130:131], v[50:51], off offset:112
	s_mov_b32 s51, 0x1a000000
	v_pk_add_f32 v[20:21], v[20:21], v[48:49] op_sel_hi:[1,0]
	v_pk_add_f32 v[22:23], v[22:23], v[48:49] op_sel_hi:[1,0]
	s_nop 2
	v_pk_add_f32 v[0:1], v[48:49], v[0:1] op_sel_hi:[0,1]
	v_pk_add_f32 v[2:3], v[48:49], v[2:3] op_sel_hi:[0,1]
	v_pk_add_f32 v[4:5], v[48:49], v[4:5] op_sel_hi:[0,1]
	s_waitcnt vmcnt(7)
	v_lshlrev_b32_e32 v56, 16, v116
	v_and_b32_e32 v57, 0xffff0000, v116
	v_pk_mul_f32 v[16:17], v[16:17], v[56:57]
	s_nop 0
	v_cvt_pk_bf16_f32 v54, v16, v17
	v_lshlrev_b32_e32 v16, 16, v117
	v_and_b32_e32 v17, 0xffff0000, v117
	v_pk_mul_f32 v[16:17], v[18:19], v[16:17]
	v_cvt_pk_bf16_f32 v55, v16, v17
	v_add_co_u32_e32 v16, vcc, s51, v52
	s_waitcnt vmcnt(6)
	v_lshlrev_b32_e32 v52, 16, v118
	v_addc_co_u32_e32 v17, vcc, 0, v53, vcc
	v_and_b32_e32 v53, 0xffff0000, v118
	v_pk_mul_f32 v[20:21], v[20:21], v[52:53]
	global_store_dwordx2 v[16:17], v[54:55], off
	v_cvt_pk_bf16_f32 v18, v20, v21
	v_lshlrev_b32_e32 v20, 16, v119
	v_and_b32_e32 v21, 0xffff0000, v119
	v_pk_mul_f32 v[20:21], v[22:23], v[20:21]
	v_pk_add_f32 v[22:23], v[24:25], v[48:49] op_sel_hi:[1,0]
	v_cvt_pk_bf16_f32 v19, v20, v21
	global_store_dwordx2 v[16:17], v[18:19], off offset:16
	s_waitcnt vmcnt(7)
	v_lshlrev_b32_e32 v20, 16, v120
	v_and_b32_e32 v21, 0xffff0000, v120
	v_pk_mul_f32 v[20:21], v[22:23], v[20:21]
	v_pk_add_f32 v[22:23], v[26:27], v[48:49] op_sel_hi:[1,0]
	v_cvt_pk_bf16_f32 v18, v20, v21
	v_lshlrev_b32_e32 v20, 16, v121
	v_and_b32_e32 v21, 0xffff0000, v121
	v_pk_mul_f32 v[20:21], v[22:23], v[20:21]
	v_pk_add_f32 v[22:23], v[28:29], v[48:49] op_sel_hi:[1,0]
	v_cvt_pk_bf16_f32 v19, v20, v21
	global_store_dwordx2 v[16:17], v[18:19], off offset:32
	s_waitcnt vmcnt(7)
	v_lshlrev_b32_e32 v20, 16, v122
	v_and_b32_e32 v21, 0xffff0000, v122
	v_pk_mul_f32 v[20:21], v[22:23], v[20:21]
	v_pk_add_f32 v[22:23], v[30:31], v[48:49] op_sel_hi:[1,0]
	v_cvt_pk_bf16_f32 v18, v20, v21
	v_lshlrev_b32_e32 v20, 16, v123
	v_and_b32_e32 v21, 0xffff0000, v123
	v_pk_mul_f32 v[20:21], v[22:23], v[20:21]
	s_nop 0
	v_cvt_pk_bf16_f32 v19, v20, v21
	global_store_dwordx2 v[16:17], v[18:19], off offset:48
	s_waitcnt vmcnt(7)
	v_lshlrev_b32_e32 v20, 16, v124
	v_and_b32_e32 v21, 0xffff0000, v124
	v_lshlrev_b32_e32 v18, 16, v125
	v_and_b32_e32 v19, 0xffff0000, v125
	v_pk_mul_f32 v[0:1], v[0:1], v[20:21]
	v_pk_mul_f32 v[2:3], v[2:3], v[18:19]
	v_cvt_pk_bf16_f32 v0, v0, v1
	v_cvt_pk_bf16_f32 v1, v2, v3
	global_store_dwordx2 v[16:17], v[0:1], off offset:64
	s_waitcnt vmcnt(7)
	v_lshlrev_b32_e32 v2, 16, v126
	v_and_b32_e32 v3, 0xffff0000, v126
	v_pk_mul_f32 v[2:3], v[4:5], v[2:3]
	v_pk_add_f32 v[4:5], v[48:49], v[6:7] op_sel_hi:[0,1]
	v_cvt_pk_bf16_f32 v0, v2, v3
	v_lshlrev_b32_e32 v2, 16, v127
	v_and_b32_e32 v3, 0xffff0000, v127
	v_pk_mul_f32 v[2:3], v[4:5], v[2:3]
	v_pk_add_f32 v[4:5], v[48:49], v[8:9] op_sel_hi:[0,1]
	v_cvt_pk_bf16_f32 v1, v2, v3
	global_store_dwordx2 v[16:17], v[0:1], off offset:80
	s_waitcnt vmcnt(7)
	v_lshlrev_b32_e32 v2, 16, v128
	v_and_b32_e32 v3, 0xffff0000, v128
	v_pk_mul_f32 v[2:3], v[4:5], v[2:3]
	v_pk_add_f32 v[4:5], v[48:49], v[10:11] op_sel_hi:[0,1]
	v_cvt_pk_bf16_f32 v0, v2, v3
	v_lshlrev_b32_e32 v2, 16, v129
	v_and_b32_e32 v3, 0xffff0000, v129
	v_pk_mul_f32 v[2:3], v[4:5], v[2:3]
	v_pk_add_f32 v[4:5], v[48:49], v[12:13] op_sel_hi:[0,1]
	v_cvt_pk_bf16_f32 v1, v2, v3
	global_store_dwordx2 v[16:17], v[0:1], off offset:96
	s_waitcnt vmcnt(7)
	v_lshlrev_b32_e32 v2, 16, v130
	v_and_b32_e32 v3, 0xffff0000, v130
	v_pk_mul_f32 v[2:3], v[4:5], v[2:3]
	v_pk_add_f32 v[4:5], v[48:49], v[14:15] op_sel_hi:[0,1]
	v_cvt_pk_bf16_f32 v0, v2, v3
	v_lshlrev_b32_e32 v2, 16, v131
	v_and_b32_e32 v3, 0xffff0000, v131
	v_pk_mul_f32 v[2:3], v[4:5], v[2:3]
	s_nop 0
	v_cvt_pk_bf16_f32 v1, v2, v3
	global_store_dwordx2 v[16:17], v[0:1], off offset:112
	global_load_dwordx4 v[116:119], v[82:83], off offset:16
	global_load_dwordx4 v[120:123], v[82:83], off
	global_load_dwordx4 v[124:127], v[98:99], off offset:-128
	global_load_dwordx4 v[128:131], v[100:101], off offset:-128
	global_load_dwordx4 v[136:139], v[82:83], off offset:80
	global_load_dwordx4 v[140:143], v[82:83], off offset:64
	global_load_dwordx4 v[144:147], v[98:99], off offset:-96
	global_load_dwordx4 v[148:151], v[100:101], off offset:-96
	global_load_dwordx4 v[152:155], v[82:83], off offset:144
	global_load_dwordx4 v[156:159], v[82:83], off offset:128
	global_load_dwordx4 v[160:163], v[98:99], off offset:-64
	global_load_dwordx4 v[164:167], v[100:101], off offset:-64
	global_load_dwordx4 v[184:187], v[82:83], off offset:208
	global_load_dwordx4 v[188:191], v[82:83], off offset:192
	global_load_dwordx4 v[192:195], v[98:99], off offset:-32
	global_load_dwordx4 v[196:199], v[100:101], off offset:-32
	global_load_dwordx4 v[200:203], v[82:83], off offset:272
	global_load_dwordx4 v[204:207], v[82:83], off offset:256
	global_load_dwordx4 v[208:211], v[98:99], off
	global_load_dwordx4 v[214:217], v[100:101], off
	global_load_dwordx4 v[218:221], v[82:83], off offset:336
	global_load_dwordx4 v[228:231], v[82:83], off offset:320
	global_load_dwordx4 v[232:235], v[98:99], off offset:32
	global_load_dwordx4 v[236:239], v[100:101], off offset:32
	s_nop 0
	s_waitcnt vmcnt(23)
	v_pk_mul_f32 v[8:9], v[32:33], v[116:117]
	s_waitcnt vmcnt(22)
	v_pk_mul_f32 v[4:5], v[36:37], v[120:121]
	v_pk_mul_f32 v[6:7], v[38:39], v[122:123]
	v_pk_mul_f32 v[10:11], v[34:35], v[118:119]
	v_cvt_pk_bf16_f32 v0, v4, v5
	v_cvt_pk_bf16_f32 v1, v6, v7
	v_cvt_pk_bf16_f32 v2, v8, v9
	v_cvt_pk_bf16_f32 v3, v10, v11
	s_waitcnt vmcnt(21)
	v_mfma_f32_32x32x16_bf16 v[16:31], v[124:127], v[0:3], 0
	s_waitcnt vmcnt(19)
	v_mul_f32_e64 v56, v44, v136
	v_mul_f32_e64 v57, v45, v137
	s_waitcnt vmcnt(18)
	v_mul_f32_e64 v52, v40, v140
	v_mul_f32_e64 v53, v41, v141
	v_pk_mul_f32 v[54:55], v[42:43], v[142:143]
	v_pk_mul_f32 v[58:59], v[46:47], v[138:139]
	v_cvt_pk_bf16_f32 v48, v52, v53
	v_cvt_pk_bf16_f32 v49, v54, v55
	v_cvt_pk_bf16_f32 v50, v56, v57
	v_cvt_pk_bf16_f32 v51, v58, v59
	v_mfma_f32_32x32x16_bf16 v[0:15], v[128:131], v[0:3], 0
	s_waitcnt vmcnt(16)
	v_mfma_f32_32x32x16_bf16 v[0:15], v[148:151], v[48:51], v[0:15]
	v_mfma_f32_32x32x16_bf16 v[16:31], v[144:147], v[48:51], v[16:31]
	ds_read_b128 v[52:55], v105 offset:128
	ds_read_b128 v[48:51], v105 offset:144
	s_waitcnt vmcnt(15) lgkmcnt(0)
	v_mul_f32_e64 v64, v152, v48
	v_mul_f32_e64 v65, v153, v49
	s_waitcnt vmcnt(14)
	v_pk_mul_f32 v[60:61], v[156:157], v[52:53]
	v_pk_mul_f32 v[62:63], v[158:159], v[54:55]
	v_pk_mul_f32 v[66:67], v[154:155], v[50:51]
	v_cvt_pk_bf16_f32 v56, v60, v61
	v_cvt_pk_bf16_f32 v57, v62, v63
	v_cvt_pk_bf16_f32 v58, v64, v65
	v_cvt_pk_bf16_f32 v59, v66, v67
	s_waitcnt vmcnt(13)
	v_mfma_f32_32x32x16_bf16 v[16:31], v[160:163], v[56:59], v[16:31]
	s_waitcnt vmcnt(12)
	v_mfma_f32_32x32x16_bf16 v[0:15], v[164:167], v[56:59], v[0:15]
	ds_read_b128 v[56:59], v105 offset:192
	s_waitcnt vmcnt(10) lgkmcnt(0)
	v_mul_f32_e64 v68, v188, v56
	v_mul_f32_e64 v69, v189, v57
	v_pk_mul_f32 v[70:71], v[190:191], v[58:59]
	ds_read_b128 v[60:63], v105 offset:208
	s_waitcnt lgkmcnt(0)
	v_pk_mul_f32 v[106:107], v[184:185], v[60:61]
	v_pk_mul_f32 v[108:109], v[186:187], v[62:63]
	v_cvt_pk_bf16_f32 v64, v68, v69
	v_cvt_pk_bf16_f32 v65, v70, v71
	v_cvt_pk_bf16_f32 v66, v106, v107
	v_cvt_pk_bf16_f32 v67, v108, v109
	s_waitcnt vmcnt(9)
	v_mfma_f32_32x32x16_bf16 v[16:31], v[192:195], v[64:67], v[16:31]
	s_waitcnt vmcnt(8)
	v_mfma_f32_32x32x16_bf16 v[0:15], v[196:199], v[64:67], v[0:15]
	s_and_saveexec_b64 s[58:59], s[8:9]
	s_cbranch_execz .LBB0_817
	ds_read_b32 v87, v105 offset:256
	s_waitcnt vmcnt(6) lgkmcnt(0)
	v_mul_f32_e32 v87, v204, v87
.LBB0_817:
	s_or_b64 exec, exec, s[58:59]
	s_waitcnt vmcnt(6)
	v_mov_b32_e32 v68, 0
	v_mov_b32_e32 v107, 0
	s_and_saveexec_b64 s[58:59], s[74:75]
	s_cbranch_execz .LBB0_819
	ds_read_b32 v106, v105 offset:260
	s_waitcnt lgkmcnt(0)
	v_mul_f32_e32 v107, v205, v106
.LBB0_819:
	s_or_b64 exec, exec, s[58:59]
	s_and_saveexec_b64 s[58:59], s[42:43]
	s_cbranch_execz .LBB0_821
	ds_read_b32 v68, v105 offset:264
	s_waitcnt lgkmcnt(0)
	v_mul_f32_e32 v68, v206, v68
.LBB0_821:
	s_or_b64 exec, exec, s[58:59]
	v_mov_b32_e32 v69, 0
	v_mov_b32_e32 v70, 0
	s_and_saveexec_b64 s[58:59], s[44:45]
	s_cbranch_execz .LBB0_823
	ds_read_b32 v70, v105 offset:268
	s_waitcnt lgkmcnt(0)
	v_mul_f32_e32 v70, v207, v70
.LBB0_823:
	s_or_b64 exec, exec, s[58:59]
	s_and_saveexec_b64 s[58:59], s[46:47]
	s_cbranch_execz .LBB0_825
	ds_read_b32 v69, v105 offset:272
	s_waitcnt lgkmcnt(0)
	v_mul_f32_e32 v69, v200, v69
.LBB0_825:
	s_or_b64 exec, exec, s[58:59]
	v_mov_b32_e32 v64, 0
	v_mov_b32_e32 v71, 0
	s_and_saveexec_b64 s[58:59], s[48:49]
	s_cbranch_execz .LBB0_827
	ds_read_b32 v71, v105 offset:276
	s_waitcnt lgkmcnt(0)
	v_mul_f32_e32 v71, v201, v71
.LBB0_827:
	s_or_b64 exec, exec, s[58:59]
	s_and_saveexec_b64 s[58:59], s[84:85]
	s_cbranch_execz .LBB0_829
	ds_read_b32 v64, v105 offset:280
	s_waitcnt lgkmcnt(0)
	v_mul_f32_e32 v64, v202, v64
.LBB0_829:
	s_or_b64 exec, exec, s[58:59]
	v_mov_b32_e32 v106, 0
	v_mov_b32_e32 v65, 0
	s_and_saveexec_b64 s[58:59], s[86:87]
	s_cbranch_execz .LBB0_831
	ds_read_b32 v65, v105 offset:284
	s_waitcnt lgkmcnt(0)
	v_mul_f32_e32 v65, v203, v65
.LBB0_831:
	s_or_b64 exec, exec, s[58:59]
	v_cvt_pk_bf16_f32 v66, v87, v107
	v_cvt_pk_bf16_f32 v67, v68, v70
	v_cvt_pk_bf16_f32 v68, v69, v71
	v_cvt_pk_bf16_f32 v69, v64, v65
	s_waitcnt vmcnt(5)
	s_nop 0
	v_mfma_f32_32x32x16_bf16 v[16:31], v[208:211], v[66:69], v[16:31]
	s_waitcnt vmcnt(4)
	v_mfma_f32_32x32x16_bf16 v[0:15], v[214:217], v[66:69], v[0:15]
	s_and_saveexec_b64 s[58:59], s[60:61]
	s_cbranch_execz .LBB0_833
	ds_read_b32 v87, v105 offset:320
	s_waitcnt vmcnt(2) lgkmcnt(0)
	v_mul_f32_e32 v106, v228, v87
.LBB0_833:
	s_or_b64 exec, exec, s[58:59]
	s_waitcnt vmcnt(2)
	v_mov_b32_e32 v68, 0
	v_mov_b32_e32 v87, 0
	s_and_saveexec_b64 s[58:59], s[90:91]
	s_cbranch_execz .LBB0_835
	ds_read_b32 v87, v105 offset:324
	s_waitcnt lgkmcnt(0)
	v_mul_f32_e32 v87, v229, v87
.LBB0_835:
	s_or_b64 exec, exec, s[58:59]
	s_and_saveexec_b64 s[58:59], s[92:93]
	s_cbranch_execz .LBB0_837
	ds_read_b32 v68, v105 offset:328
	s_waitcnt lgkmcnt(0)
	v_mul_f32_e32 v68, v230, v68
.LBB0_837:
	s_or_b64 exec, exec, s[58:59]
	v_mov_b32_e32 v69, 0
	v_mov_b32_e32 v70, 0
	s_and_saveexec_b64 s[58:59], s[94:95]
	s_cbranch_execz .LBB0_839
	ds_read_b32 v70, v105 offset:332
	s_waitcnt lgkmcnt(0)
	v_mul_f32_e32 v70, v231, v70
.LBB0_839:
	s_or_b64 exec, exec, s[58:59]
	s_and_saveexec_b64 s[58:59], s[96:97]
	s_cbranch_execz .LBB0_841
	ds_read_b32 v69, v105 offset:336
	s_waitcnt lgkmcnt(0)
	v_mul_f32_e32 v69, v218, v69
.LBB0_841:
	s_or_b64 exec, exec, s[58:59]
	v_mov_b32_e32 v64, 0
	v_mov_b32_e32 v71, 0
	s_and_saveexec_b64 s[58:59], s[4:5]
	s_cbranch_execz .LBB0_843
	ds_read_b32 v71, v105 offset:340
	s_waitcnt lgkmcnt(0)
	v_mul_f32_e32 v71, v219, v71
.LBB0_843:
	s_or_b64 exec, exec, s[58:59]
	s_and_saveexec_b64 s[58:59], s[6:7]
	s_cbranch_execz .LBB0_845
	ds_read_b32 v64, v105 offset:344
	s_waitcnt lgkmcnt(0)
	v_mul_f32_e32 v64, v220, v64
.LBB0_845:
	s_or_b64 exec, exec, s[58:59]
	v_mov_b32_e32 v65, 0
	v_mov_b32_e32 v66, 0
	s_and_saveexec_b64 s[58:59], s[2:3]
	s_cbranch_execz .LBB0_847
	ds_read_b32 v66, v105 offset:348
	s_waitcnt lgkmcnt(0)
	v_mul_f32_e32 v66, v221, v66
.LBB0_847:
	s_or_b64 exec, exec, s[58:59]
	v_cvt_pk_bf16_f32 v107, v68, v70
	v_cvt_pk_bf16_f32 v108, v69, v71
	v_cvt_pk_bf16_f32 v109, v64, v66
	v_cvt_pk_bf16_f32 v106, v106, v87
	s_mov_b32 s51, 0xc010000
	global_load_dword v64, v[76:77], off offset:256
	s_waitcnt vmcnt(2)
	v_mfma_f32_32x32x16_bf16 v[16:31], v[232:235], v[106:109], v[16:31]
	v_add_co_u32_e32 v66, vcc, s51, v102
	s_mov_b32 s51, 0x1a010000
	s_nop 0
	v_addc_co_u32_e32 v67, vcc, 0, v103, vcc
	global_load_dwordx2 v[116:117], v[66:67], off
	global_load_dwordx2 v[118:119], v[66:67], off offset:16
	global_load_dwordx2 v[120:121], v[66:67], off offset:32
	global_load_dwordx2 v[122:123], v[66:67], off offset:48
	global_load_dwordx2 v[124:125], v[66:67], off offset:64
	global_load_dwordx2 v[126:127], v[66:67], off offset:80
	global_load_dwordx2 v[128:129], v[66:67], off offset:96
	global_load_dwordx2 v[130:131], v[66:67], off offset:112
	s_waitcnt vmcnt(1)
	s_nop 5
	v_pk_add_f32 v[16:17], v[16:17], v[64:65] op_sel_hi:[1,0]
	v_pk_add_f32 v[18:19], v[18:19], v[64:65] op_sel_hi:[1,0]
	v_pk_add_f32 v[20:21], v[20:21], v[64:65] op_sel_hi:[1,0]
	v_pk_add_f32 v[22:23], v[22:23], v[64:65] op_sel_hi:[1,0]
	v_mfma_f32_32x32x16_bf16 v[0:15], v[236:239], v[106:109], v[0:15]
	s_waitcnt vmcnt(7)
	v_lshlrev_b32_e32 v70, 16, v116
	v_and_b32_e32 v71, 0xffff0000, v116
	v_mul_f32_e64 v16, v16, v70
	v_mul_f32_e64 v17, v17, v71
	s_nop 6
	v_pk_add_f32 v[0:1], v[64:65], v[0:1] op_sel_hi:[0,1]
	v_cvt_pk_bf16_f32 v68, v16, v17
	v_lshlrev_b32_e32 v16, 16, v117
	v_and_b32_e32 v17, 0xffff0000, v117
	v_pk_mul_f32 v[16:17], v[18:19], v[16:17]
	v_cvt_pk_bf16_f32 v69, v16, v17
	v_add_co_u32_e32 v16, vcc, s51, v102
	v_pk_add_f32 v[2:3], v[64:65], v[2:3] op_sel_hi:[0,1]
	s_nop 0
	v_addc_co_u32_e32 v17, vcc, 0, v103, vcc
	global_store_dwordx2 v[16:17], v[68:69], off
	v_pk_add_f32 v[4:5], v[64:65], v[4:5] op_sel_hi:[0,1]
	s_waitcnt vmcnt(7)
	v_lshlrev_b32_e32 v68, 16, v118
	v_and_b32_e32 v69, 0xffff0000, v118
	v_pk_mul_f32 v[20:21], v[20:21], v[68:69]
	s_nop 0
	v_cvt_pk_bf16_f32 v18, v20, v21
	v_lshlrev_b32_e32 v20, 16, v119
	v_and_b32_e32 v21, 0xffff0000, v119
	v_pk_mul_f32 v[20:21], v[22:23], v[20:21]
	v_pk_add_f32 v[22:23], v[24:25], v[64:65] op_sel_hi:[1,0]
	v_cvt_pk_bf16_f32 v19, v20, v21
	global_store_dwordx2 v[16:17], v[18:19], off offset:16
	s_waitcnt vmcnt(7)
	v_lshlrev_b32_e32 v20, 16, v120
	v_and_b32_e32 v21, 0xffff0000, v120
	v_pk_mul_f32 v[20:21], v[22:23], v[20:21]
	v_pk_add_f32 v[22:23], v[26:27], v[64:65] op_sel_hi:[1,0]
	v_cvt_pk_bf16_f32 v18, v20, v21
	v_lshlrev_b32_e32 v20, 16, v121
	v_and_b32_e32 v21, 0xffff0000, v121
	v_pk_mul_f32 v[20:21], v[22:23], v[20:21]
	v_pk_add_f32 v[22:23], v[28:29], v[64:65] op_sel_hi:[1,0]
	v_cvt_pk_bf16_f32 v19, v20, v21
	global_store_dwordx2 v[16:17], v[18:19], off offset:32
	s_waitcnt vmcnt(7)
	v_lshlrev_b32_e32 v20, 16, v122
	v_and_b32_e32 v21, 0xffff0000, v122
	v_pk_mul_f32 v[20:21], v[22:23], v[20:21]
	v_pk_add_f32 v[22:23], v[30:31], v[64:65] op_sel_hi:[1,0]
	v_cvt_pk_bf16_f32 v18, v20, v21
	v_lshlrev_b32_e32 v20, 16, v123
	v_and_b32_e32 v21, 0xffff0000, v123
	v_pk_mul_f32 v[20:21], v[22:23], v[20:21]
	s_nop 0
	v_cvt_pk_bf16_f32 v19, v20, v21
	global_store_dwordx2 v[16:17], v[18:19], off offset:48
	s_waitcnt vmcnt(7)
	v_lshlrev_b32_e32 v20, 16, v124
	v_and_b32_e32 v21, 0xffff0000, v124
	v_lshlrev_b32_e32 v18, 16, v125
	v_and_b32_e32 v19, 0xffff0000, v125
	v_pk_mul_f32 v[0:1], v[0:1], v[20:21]
	v_pk_mul_f32 v[2:3], v[2:3], v[18:19]
	v_cvt_pk_bf16_f32 v0, v0, v1
	v_cvt_pk_bf16_f32 v1, v2, v3
	global_store_dwordx2 v[16:17], v[0:1], off offset:64
	s_waitcnt vmcnt(7)
	v_lshlrev_b32_e32 v2, 16, v126
	v_and_b32_e32 v3, 0xffff0000, v126
	v_pk_mul_f32 v[2:3], v[4:5], v[2:3]
	v_pk_add_f32 v[4:5], v[64:65], v[6:7] op_sel_hi:[0,1]
	v_cvt_pk_bf16_f32 v0, v2, v3
	v_lshlrev_b32_e32 v2, 16, v127
	v_and_b32_e32 v3, 0xffff0000, v127
	v_pk_mul_f32 v[2:3], v[4:5], v[2:3]
	v_pk_add_f32 v[4:5], v[64:65], v[8:9] op_sel_hi:[0,1]
	v_cvt_pk_bf16_f32 v1, v2, v3
	global_store_dwordx2 v[16:17], v[0:1], off offset:80
	s_waitcnt vmcnt(7)
	v_lshlrev_b32_e32 v2, 16, v128
	v_and_b32_e32 v3, 0xffff0000, v128
	v_pk_mul_f32 v[2:3], v[4:5], v[2:3]
	v_pk_add_f32 v[4:5], v[64:65], v[10:11] op_sel_hi:[0,1]
	v_cvt_pk_bf16_f32 v0, v2, v3
	v_lshlrev_b32_e32 v2, 16, v129
	v_and_b32_e32 v3, 0xffff0000, v129
	v_pk_mul_f32 v[2:3], v[4:5], v[2:3]
	v_pk_add_f32 v[4:5], v[64:65], v[12:13] op_sel_hi:[0,1]
	v_cvt_pk_bf16_f32 v1, v2, v3
	global_store_dwordx2 v[16:17], v[0:1], off offset:96
	s_waitcnt vmcnt(7)
	v_lshlrev_b32_e32 v2, 16, v130
	v_and_b32_e32 v3, 0xffff0000, v130
	v_pk_mul_f32 v[2:3], v[4:5], v[2:3]
	v_pk_add_f32 v[4:5], v[64:65], v[14:15] op_sel_hi:[0,1]
	v_cvt_pk_bf16_f32 v0, v2, v3
	v_lshlrev_b32_e32 v2, 16, v131
	v_and_b32_e32 v3, 0xffff0000, v131
	v_pk_mul_f32 v[2:3], v[4:5], v[2:3]
	s_nop 0
	v_cvt_pk_bf16_f32 v1, v2, v3
	global_store_dwordx2 v[16:17], v[0:1], off offset:112
	global_load_dwordx4 v[0:3], v[84:85], off offset:16
	s_nop 0
	global_load_dwordx4 v[4:7], v[84:85], off
	s_waitcnt vmcnt(1)
	v_pk_mul_f32 v[8:9], v[32:33], v[0:1]
	s_waitcnt vmcnt(0)
	v_pk_mul_f32 v[4:5], v[36:37], v[4:5]
	v_pk_mul_f32 v[6:7], v[38:39], v[6:7]
	v_pk_mul_f32 v[10:11], v[34:35], v[2:3]
	v_cvt_pk_bf16_f32 v0, v4, v5
	v_cvt_pk_bf16_f32 v1, v6, v7
	v_cvt_pk_bf16_f32 v2, v8, v9
	v_cvt_pk_bf16_f32 v3, v10, v11
	global_load_dwordx4 v[4:7], v[98:99], off offset:-128
	global_load_dwordx4 v[8:11], v[100:101], off offset:-128
	global_load_dwordx4 v[32:35], v[84:85], off offset:80
	global_load_dwordx4 v[36:39], v[84:85], off offset:64
	s_waitcnt vmcnt(3)
	v_mfma_f32_32x32x16_bf16 v[16:31], v[4:7], v[0:3], 0
	s_waitcnt vmcnt(0)
	v_mul_f32_e64 v36, v40, v36
	v_mul_f32_e64 v37, v41, v37
	v_mul_f32_e64 v38, v42, v38
	v_mul_f32_e64 v39, v43, v39
	v_pk_mul_f32 v[40:41], v[44:45], v[32:33]
	v_pk_mul_f32 v[42:43], v[46:47], v[34:35]
	v_cvt_pk_bf16_f32 v32, v36, v37
	v_cvt_pk_bf16_f32 v33, v38, v39
	v_cvt_pk_bf16_f32 v34, v40, v41
	v_cvt_pk_bf16_f32 v35, v42, v43
	global_load_dwordx4 v[36:39], v[98:99], off offset:-96
	global_load_dwordx4 v[40:43], v[100:101], off offset:-96
	v_mfma_f32_32x32x16_bf16 v[0:15], v[8:11], v[0:3], 0
	s_waitcnt vmcnt(1)
	v_mfma_f32_32x32x16_bf16 v[16:31], v[36:39], v[32:35], v[16:31]
	s_waitcnt vmcnt(0)
	v_mfma_f32_32x32x16_bf16 v[0:15], v[40:43], v[32:35], v[0:15]
	global_load_dwordx4 v[32:35], v[84:85], off offset:144
	global_load_dwordx4 v[36:39], v[84:85], off offset:128
	s_waitcnt vmcnt(1)
	v_mul_f32_e64 v40, v48, v32
	v_mul_f32_e64 v41, v49, v33
	s_waitcnt vmcnt(0)
	v_pk_mul_f32 v[36:37], v[52:53], v[36:37]
	v_pk_mul_f32 v[38:39], v[54:55], v[38:39]
	v_pk_mul_f32 v[42:43], v[50:51], v[34:35]
	v_cvt_pk_bf16_f32 v32, v36, v37
	v_cvt_pk_bf16_f32 v33, v38, v39
	v_cvt_pk_bf16_f32 v34, v40, v41
	v_cvt_pk_bf16_f32 v35, v42, v43
	global_load_dwordx4 v[36:39], v[98:99], off offset:-64
	global_load_dwordx4 v[40:43], v[100:101], off offset:-64
	s_waitcnt vmcnt(1)
	v_mfma_f32_32x32x16_bf16 v[16:31], v[36:39], v[32:35], v[16:31]
	s_waitcnt vmcnt(0)
	v_mfma_f32_32x32x16_bf16 v[0:15], v[40:43], v[32:35], v[0:15]
	global_load_dwordx4 v[32:35], v[84:85], off offset:208
	global_load_dwordx4 v[36:39], v[84:85], off offset:192
	s_waitcnt vmcnt(1)
	v_mul_f32_e64 v40, v60, v32
	v_mul_f32_e64 v41, v61, v33
	s_waitcnt vmcnt(0)
	v_pk_mul_f32 v[36:37], v[56:57], v[36:37]
	v_pk_mul_f32 v[38:39], v[58:59], v[38:39]
	v_pk_mul_f32 v[42:43], v[62:63], v[34:35]
	v_cvt_pk_bf16_f32 v32, v36, v37
	v_cvt_pk_bf16_f32 v33, v38, v39
	v_cvt_pk_bf16_f32 v34, v40, v41
	v_cvt_pk_bf16_f32 v35, v42, v43
	global_load_dwordx4 v[36:39], v[98:99], off offset:-32
	global_load_dwordx4 v[40:43], v[100:101], off offset:-32
	s_waitcnt vmcnt(1)
	v_mfma_f32_32x32x16_bf16 v[16:31], v[36:39], v[32:35], v[16:31]
	s_waitcnt vmcnt(0)
	v_mfma_f32_32x32x16_bf16 v[0:15], v[40:43], v[32:35], v[0:15]
	global_load_dwordx4 v[32:35], v[84:85], off offset:272
	global_load_dwordx4 v[36:39], v[84:85], off offset:256
	ds_read_b128 v[40:43], v105 offset:256
	ds_read_b128 v[44:47], v105 offset:272
	s_waitcnt vmcnt(0) lgkmcnt(1)
	v_pk_mul_f32 v[36:37], v[36:37], v[40:41]
	v_pk_mul_f32 v[38:39], v[38:39], v[42:43]
	s_waitcnt lgkmcnt(0)
	v_pk_mul_f32 v[40:41], v[32:33], v[44:45]
	v_pk_mul_f32 v[42:43], v[34:35], v[46:47]
	v_cvt_pk_bf16_f32 v32, v36, v37
	v_cvt_pk_bf16_f32 v33, v38, v39
	v_cvt_pk_bf16_f32 v34, v40, v41
	v_cvt_pk_bf16_f32 v35, v42, v43
	global_load_dwordx4 v[36:39], v[98:99], off
	global_load_dwordx4 v[40:43], v[100:101], off
	s_waitcnt vmcnt(1)
	v_mfma_f32_32x32x16_bf16 v[16:31], v[36:39], v[32:35], v[16:31]
	s_waitcnt vmcnt(0)
	v_mfma_f32_32x32x16_bf16 v[0:15], v[40:43], v[32:35], v[0:15]
	global_load_dwordx4 v[32:35], v[84:85], off offset:336
	global_load_dwordx4 v[36:39], v[84:85], off offset:320
	ds_read_b128 v[40:43], v105 offset:320
	s_waitcnt vmcnt(0) lgkmcnt(0)
	v_mul_f32_e64 v40, v36, v40
	v_mul_f32_e64 v41, v37, v41
	v_pk_mul_f32 v[42:43], v[38:39], v[42:43]
	ds_read_b128 v[36:39], v105 offset:336
	s_waitcnt lgkmcnt(0)
	v_pk_mul_f32 v[36:37], v[32:33], v[36:37]
	v_pk_mul_f32 v[38:39], v[34:35], v[38:39]
	v_cvt_pk_bf16_f32 v32, v40, v41
	v_cvt_pk_bf16_f32 v33, v42, v43
	v_cvt_pk_bf16_f32 v34, v36, v37
	v_cvt_pk_bf16_f32 v35, v38, v39
	global_load_dwordx4 v[36:39], v[98:99], off offset:32
	global_load_dwordx4 v[40:43], v[100:101], off offset:32
	s_waitcnt vmcnt(1)
	v_mfma_f32_32x32x16_bf16 v[16:31], v[36:39], v[32:35], v[16:31]
	s_waitcnt vmcnt(0)
	v_mfma_f32_32x32x16_bf16 v[0:15], v[40:43], v[32:35], v[0:15]
	global_load_dwordx4 v[32:35], v[84:85], off offset:400
	global_load_dwordx4 v[36:39], v[84:85], off offset:384
	s_and_saveexec_b64 s[58:59], s[0:1]
	s_cbranch_execz .LBB0_849
	ds_read_b32 v40, v105 offset:384
	s_waitcnt vmcnt(0) lgkmcnt(0)
	v_mul_f32_e32 v65, v36, v40
